# RWKV-7 state scan: second chunk step's seven decay-vector LDS reads issued with the record fragment reads before the mid barrier (spare registers) instead of seven read-wait round trips
# speedup vs baseline: 1.0087x; 1.0087x over previous
.LBB0_433:
	s_mul_i32 s1, s0, 37
	s_bfe_u32 s2, s1, 0x80008
	s_lshr_b32 s1, s1, 8
	s_sub_i32 s1, s0, s1
	s_bfe_u32 s1, s1, 0x70001
	s_add_i32 s1, s1, s2
	s_bfe_u32 s1, s1, 0x60002
	s_mul_i32 s1, s1, 7
	s_sub_i32 s1, s0, s1
	s_and_b32 s1, s1, 0xff
	s_mulk_i32 s1, 0x4800
	v_add_u32_e32 v136, s1, v151
	v_cvt_pk_bf16_f32 v112, v16, v17
	v_cvt_pk_bf16_f32 v113, v18, v19
	v_cvt_pk_bf16_f32 v114, v20, v21
	v_cvt_pk_bf16_f32 v115, v22, v23
	v_cvt_pk_bf16_f32 v116, v24, v25
	v_cvt_pk_bf16_f32 v117, v26, v27
	v_cvt_pk_bf16_f32 v118, v28, v29
	v_cvt_pk_bf16_f32 v119, v30, v31
	v_cvt_pk_bf16_f32 v120, v0, v1
	v_cvt_pk_bf16_f32 v121, v2, v3
	v_cvt_pk_bf16_f32 v122, v4, v5
	v_cvt_pk_bf16_f32 v123, v6, v7
	v_cvt_pk_bf16_f32 v124, v8, v9
	v_cvt_pk_bf16_f32 v125, v10, v11
	v_cvt_pk_bf16_f32 v126, v12, v13
	v_cvt_pk_bf16_f32 v127, v14, v15
	ds_read_b128 v[32:35], v136 offset:17792
	ds_read_b128 v[36:39], v136 offset:17824
	ds_read_b128 v[40:43], v136 offset:17856
	ds_read_b128 v[128:131], v136 offset:17920
	ds_read_b128 v[132:135], v136 offset:17952
	s_waitcnt lgkmcnt(0)
	v_pk_mul_f32 v[16:17], v[16:17], v[32:33]
	v_pk_mul_f32 v[18:19], v[18:19], v[34:35]
	ds_read_b128 v[32:35], v136 offset:17888
	v_pk_mul_f32 v[20:21], v[20:21], v[36:37]
	v_pk_mul_f32 v[22:23], v[22:23], v[38:39]
	v_pk_mul_f32 v[24:25], v[24:25], v[40:41]
	v_pk_mul_f32 v[26:27], v[26:27], v[42:43]
	s_waitcnt lgkmcnt(0)
	v_pk_mul_f32 v[28:29], v[28:29], v[32:33]
	v_pk_mul_f32 v[30:31], v[30:31], v[34:35]
	v_mfma_f32_32x32x16_bf16 v[32:47], v[48:51], v[112:115], 0
	v_mul_f32_e64 v0, v0, v128
	v_mul_f32_e64 v1, v1, v129
	v_mul_f32_e64 v2, v2, v130
	v_mul_f32_e64 v3, v3, v131
	v_mul_f32_e64 v4, v4, v132
	v_mul_f32_e64 v5, v5, v133
	v_pk_mul_f32 v[6:7], v[6:7], v[134:135]
	ds_read_b128 v[128:131], v136 offset:17984
	ds_read_b128 v[132:135], v136 offset:18016
	s_or_b32 s1, s0, 1
	v_mfma_f32_32x32x16_bf16 v[16:31], v[72:75], v[112:115], v[16:31]
	s_and_b32 s2, s1, 0xff
	s_waitcnt lgkmcnt(0)
	v_mul_f32_e64 v8, v8, v128
	v_mul_f32_e64 v9, v9, v129
	v_mul_f32_e64 v10, v10, v130
	v_mul_f32_e64 v11, v11, v131
	v_pk_mul_f32 v[12:13], v[12:13], v[132:133]
	v_pk_mul_f32 v[14:15], v[14:15], v[134:135]
	s_mul_i32 s2, s2, 37
	s_lshr_b32 s2, s2, 8
	v_mfma_f32_32x32x16_bf16 v[32:47], v[52:55], v[116:119], v[32:47]
	s_sub_i32 s3, s1, s2
	s_bfe_u32 s3, s3, 0x70001
	s_add_i32 s3, s3, s2
	s_lshr_b32 s2, s3, 2
	s_mul_i32 s2, s2, 7
	s_sub_i32 s1, s1, s2
	s_and_b32 s1, s1, 0xff
	v_mfma_f32_32x32x16_bf16 v[0:15], v[88:91], v[112:115], v[0:15]
	s_mulk_i32 s1, 0x4800
	s_add_i32 s1, s1, 0
	v_add_u32_e32 v192, s1, v144
	v_add_u32_e32 v180, v192, v156
	s_cmpk_gt_u32 s0, 0x7d
	s_cselect_b64 s[2:3], -1, 0
	v_mfma_f32_32x32x16_bf16 v[16:31], v[76:79], v[116:119], v[16:31]
	s_and_b64 vcc, exec, s[2:3]
	v_mfma_f32_32x32x16_bf16 v[32:47], v[56:59], v[120:123], v[32:47]
	v_mfma_f32_32x32x16_bf16 v[0:15], v[92:95], v[116:119], v[0:15]
	v_mfma_f32_32x32x16_bf16 v[16:31], v[80:83], v[120:123], v[16:31]
	v_mfma_f32_32x32x16_bf16 v[32:47], v[60:63], v[124:127], v[32:47]
	v_mfma_f32_32x32x16_bf16 v[0:15], v[96:99], v[120:123], v[0:15]
	v_mfma_f32_32x32x16_bf16 v[16:31], v[84:87], v[124:127], v[16:31]
	v_mfma_f32_32x32x16_bf16 v[32:47], v[68:71], v[64:67], v[32:47]
	v_mfma_f32_32x32x16_bf16 v[0:15], v[100:103], v[124:127], v[0:15]
	s_nop 10
	v_add_u32_e32 v45, s1, v153
	v_add_u32_e32 v46, v45, v152
	v_add_u32_e32 v160, v45, v155
	v_add_u32_e32 v44, v192, v150
	ds_read2_b64 v[40:43], v46 offset1:2
	ds_read2_b64 v[116:119], v46 offset0:4 offset1:6
	ds_read2_b64 v[120:123], v46 offset0:8 offset1:10
	ds_read2_b64 v[124:127], v46 offset0:12 offset1:14
	v_add_u32_e32 v46, v192, v154
	v_add_u32_e32 v132, 0x800, v160
	v_mfma_f32_32x32x16_bf16 v[16:31], v[104:107], v[64:67], v[16:31]
	v_add_u32_e32 v172, 0x1800, v160
	ds_read_b128 v[112:115], v44 offset:14720
	ds_read_b128 v[128:131], v46 offset:2176
	ds_read2_b64 v[44:47], v132 offset0:112 offset1:114
	ds_read2_b64 v[140:143], v132 offset0:116 offset1:118
	ds_read2_b64 v[136:139], v132 offset0:120 offset1:122
	ds_read2_b64 v[132:135], v132 offset0:124 offset1:126
	ds_read2_b64 v[160:163], v172 offset0:144 offset1:146
	ds_read2_b64 v[164:167], v172 offset0:148 offset1:150
	ds_read2_b64 v[168:171], v172 offset0:152 offset1:154
	ds_read2_b64 v[172:175], v172 offset0:156 offset1:158
	ds_read_b128 v[176:179], v180 offset:11648
	ds_read_b128 v[180:183], v180 offset:13184
	ds_read_b128 v[220:223], v192 offset:17888
	ds_read_b128 v[224:227], v192 offset:17856
	ds_read_b128 v[228:231], v192 offset:17824
	ds_read_b128 v[232:235], v192 offset:17792
	ds_read_b128 v[236:239], v192 offset:18016
	ds_read_b128 v[240:243], v192 offset:17984
	ds_read_b128 v[244:247], v192 offset:17952
	ds_write2st64_b32 v158, v32, v33 offset1:1
	ds_write2st64_b32 v158, v34, v35 offset0:2 offset1:3
	ds_write2st64_b32 v158, v36, v37 offset0:8 offset1:9
	ds_write2st64_b32 v158, v38, v39 offset0:10 offset1:11
	s_waitcnt lgkmcnt(0)
	s_barrier
	ds_read_b128 v[36:39], v192 offset:17920
	v_cvt_pk_bf16_f32 v32, v16, v17
	v_mfma_f32_32x32x16_bf16 v[0:15], v[108:111], v[64:67], v[0:15]
	v_cvt_pk_bf16_f32 v33, v18, v19
	v_cvt_pk_bf16_f32 v34, v20, v21
	v_cvt_pk_bf16_f32 v35, v22, v23
	v_cvt_pk_bf16_f32 v184, v24, v25
	v_cvt_pk_bf16_f32 v185, v26, v27
	v_cvt_pk_bf16_f32 v186, v28, v29
	v_cvt_pk_bf16_f32 v187, v30, v31
	v_cvt_pk_bf16_f32 v188, v0, v1
	v_cvt_pk_bf16_f32 v189, v2, v3
	v_cvt_pk_bf16_f32 v190, v4, v5
	v_cvt_pk_bf16_f32 v191, v6, v7
	v_cvt_pk_bf16_f32 v216, v8, v9
	v_cvt_pk_bf16_f32 v217, v10, v11
	v_cvt_pk_bf16_f32 v218, v12, v13
	v_cvt_pk_bf16_f32 v219, v14, v15
	v_pk_mul_f32 v[28:29], v[28:29], v[220:221]
	v_pk_mul_f32 v[30:31], v[30:31], v[222:223]
	v_pk_mul_f32 v[24:25], v[24:25], v[224:225]
	v_pk_mul_f32 v[26:27], v[26:27], v[226:227]
	v_pk_mul_f32 v[20:21], v[20:21], v[228:229]
	v_pk_mul_f32 v[22:23], v[22:23], v[230:231]
	v_pk_mul_f32 v[18:19], v[18:19], v[234:235]
	v_pk_mul_f32 v[16:17], v[16:17], v[232:233]
	v_pk_mul_f32 v[12:13], v[12:13], v[236:237]
	v_pk_mul_f32 v[14:15], v[14:15], v[238:239]
	v_mfma_f32_32x32x16_bf16 v[16:31], v[44:47], v[32:35], v[16:31]
	v_mul_f32_e64 v8, v8, v240
	v_mul_f32_e64 v9, v9, v241
	v_mul_f32_e64 v10, v10, v242
	v_mul_f32_e64 v11, v11, v243
	v_pk_mul_f32 v[4:5], v[4:5], v[244:245]
	v_pk_mul_f32 v[6:7], v[6:7], v[246:247]
	v_mfma_f32_32x32x16_bf16 v[16:31], v[140:143], v[184:187], v[16:31]
	s_waitcnt lgkmcnt(0)
	v_mul_f32_e64 v2, v2, v38
	v_mul_f32_e64 v3, v3, v39
	v_mul_f32_e64 v0, v0, v36
	v_mul_f32_e64 v1, v1, v37
	s_nop 1
	v_mfma_f32_32x32x16_bf16 v[0:15], v[160:163], v[32:35], v[0:15]
	v_mfma_f32_32x32x16_bf16 v[32:47], v[40:43], v[32:35], 0
	v_mfma_f32_32x32x16_bf16 v[32:47], v[116:119], v[184:187], v[32:47]
	v_mfma_f32_32x32x16_bf16 v[0:15], v[164:167], v[184:187], v[0:15]
	v_mfma_f32_32x32x16_bf16 v[32:47], v[120:123], v[188:191], v[32:47]
	v_mfma_f32_32x32x16_bf16 v[16:31], v[136:139], v[188:191], v[16:31]
	v_mfma_f32_32x32x16_bf16 v[0:15], v[168:171], v[188:191], v[0:15]
	v_mfma_f32_32x32x16_bf16 v[32:47], v[124:127], v[216:219], v[32:47]
	v_mfma_f32_32x32x16_bf16 v[16:31], v[132:135], v[216:219], v[16:31]
	v_mfma_f32_32x32x16_bf16 v[0:15], v[172:175], v[216:219], v[0:15]
	v_mfma_f32_32x32x16_bf16 v[32:47], v[128:131], v[112:115], v[32:47]
	v_mfma_f32_32x32x16_bf16 v[16:31], v[176:179], v[112:115], v[16:31]
	v_mfma_f32_32x32x16_bf16 v[0:15], v[180:183], v[112:115], v[0:15]
	s_cbranch_vccnz .LBB0_432
	s_add_i32 s1, s0, 2
	s_and_b32 s4, s1, 0xff
	s_mul_i32 s4, s4, 37
	s_lshr_b32 s5, s4, 8
	s_sub_i32 s5, s1, s5
	s_bfe_u32 s5, s5, 0x70001
	s_bfe_u32 s4, s4, 0x80008
	s_add_i32 s5, s5, s4
	s_bfe_u32 s4, s5, 0x60002
	s_mul_i32 s4, s4, 7
	s_sub_i32 s1, s1, s4
	s_and_b32 s1, s1, 0xff
	s_mulk_i32 s1, 0x4800
	s_add_i32 s1, s1, 0
	v_add_u32_e32 v40, s1, v144
	v_add_u32_e32 v42, s1, v153
	v_add_u32_e32 v41, v40, v150
	v_add_u32_e32 v43, v42, v152
	ds_read2_b64 v[48:51], v43 offset1:2
	ds_read2_b64 v[52:55], v43 offset0:4 offset1:6
	ds_read2_b64 v[56:59], v43 offset0:8 offset1:10
	ds_read2_b64 v[60:63], v43 offset0:12 offset1:14
	v_add_u32_e32 v43, v40, v154
	ds_read_b128 v[64:67], v41 offset:14720
	ds_read_b128 v[68:71], v43 offset:2176
	v_add_u32_e32 v41, v42, v155
	v_add_u32_e32 v42, 0x800, v41
	v_add_u32_e32 v41, 0x1800, v41
	ds_read2_b64 v[72:75], v42 offset0:112 offset1:114
	ds_read2_b64 v[76:79], v42 offset0:116 offset1:118
	ds_read2_b64 v[80:83], v42 offset0:120 offset1:122
	ds_read2_b64 v[84:87], v42 offset0:124 offset1:126
	v_add_u32_e32 v40, v40, v156
	ds_read2_b64 v[88:91], v41 offset0:144 offset1:146
	ds_read2_b64 v[92:95], v41 offset0:148 offset1:150
	ds_read2_b64 v[96:99], v41 offset0:152 offset1:154
	ds_read2_b64 v[100:103], v41 offset0:156 offset1:158
	ds_read_b128 v[104:107], v40 offset:11648
	ds_read_b128 v[108:111], v40 offset:13184
	s_branch .LBB0_432
